# combo19: combo11 + diff-attention off-diagonal tiles prefetch all 16 V fragments into free VGPRs right after the last K-fragment reads (PV MFMAs no longer wait on just-issued LDS reads)
# speedup vs baseline: 1.0117x; 1.0099x over previous
; template <int TYPE> __device__ __forceinline__ void attn_unit(const AttnCtx& C, int b, int h, int qb, LAS unsigned char* lds, int tid_in, unsigned* counter) {
;     ...
;             const bool active = (TYPE == 2) ? (t >= cq - 8 && t <= cq) : (TYPE == 0) ? (t <= cq && (float)(256 * qb + 32 * w - 64 * t - 63) < dmax) : (t <= cq && t >= tfirst);
;             if (active) {
;                 f32x16 p0, p1;
;                 const LAS unsigned char* kp = Kb + bo + hi * 1024 + r32 * 16;
; #pragma unroll
;                 for (int d0 = 0; d0 < 4; ++d0) {
;                     const bf16x8 a0 = *(const LAS bf16x8*)(kp + d0 * 2048), a1 = *(const LAS bf16x8*)(kp + d0 * 2048 + 512);
;                     if (d0 == 0) { p0 = MFMA32(a0, qr[0], (TYPE == 1 ? cvec : zvec)); p1 = MFMA32(a1, qr[0], (TYPE == 1 ? cvec : zvec)); }
;                     else { p0 = MFMA32(a0, qr[d0], p0); p1 = MFMA32(a1, qr[d0], p1); }
;                 }
;                 const int xi = sq - 64 * t - 4 * hi;
;                 if (TYPE == 0) {
;                     const float xf = (float)xi;
; #pragma unroll
;                     for (int r = 0; r < 16; ++r) { const float c = (float)((r & 3) + 8 * (r >> 2));
;                         p0[r] = fast_exp2(p0[r] - sl2 * fabsf(xf - c)); p1[r] = fast_exp2(p1[r] - sl2 * fabsf(xf - (c + 32.f))); }
;                 } else if (TYPE == 1) {
;                     const LAS float* fp = Fb + (t & 3) * 64 + 4 * hi;
; #pragma unroll
;                     for (int g = 0; g < 4; ++g) { const f32x4 fa = *(const LAS f32x4*)(fp + 8 * g), fb2 = *(const LAS f32x4*)(fp + 32 + 8 * g);
; #pragma unroll
;                         for (int i = 0; i < 4; i += 2) {
;                             const f32x2_t d0_ = (f32x2_t){p0[4 * g + i], p0[4 * g + i + 1]} - (f32x2_t){fa[i], fa[i + 1]}, d1_ = (f32x2_t){p1[4 * g + i], p1[4 * g + i + 1]} - (f32x2_t){fb2[i], fb2[i + 1]};
;                             p0[4 * g + i] = fast_exp2(d0_[0]); p0[4 * g + i + 1] = fast_exp2(d0_[1]); p1[4 * g + i] = fast_exp2(d1_[0]); p1[4 * g + i + 1] = fast_exp2(d1_[1]); } }
;                     if (t == cq) { const int qrel = 32 * (w & 1) + r32;
; #pragma unroll
;                         for (int r = 0; r < 16; ++r) { const int kv = crow(r, hi); if (kv > qrel) p0[r] = 0.f; if (kv + 32 > qrel) p1[r] = 0.f; } }
;                 } else {
;                     if (cq - t >= 3) { const float bc = relb[256];
.LBB0_438:
	s_cmp_gt_i32 s4, s14
	s_cbranch_scc1 .LBB0_433
	s_sub_i32 s6, s1, 63
	v_cvt_f32_i32_e32 v32, s6
	v_cmp_ngt_f32_e32 vcc, v168, v32
	s_cbranch_vccnz .LBB0_433
	s_cmp_eq_u32 s4, s14
	s_cbranch_scc1 .Lt0diag_4
	v_add_u32_e32 v118, s5, v171
	v_add_u32_e32 v213, s1, v172
	v_cvt_f32_i32_e32 v213, v213
	v_mul_f32_e64 v210, -v167, v213
	ds_read_b128 v[202:205], v118
	ds_read_b128 v[206:209], v118 offset:512
	ds_read_b128 v[110:113], v118 offset:2048
	ds_read_b128 v[114:117], v118 offset:2560
	v_add_u32_e32 v134, s5, v170
	v_mov_b32_e32 v48, v210
	v_fmamk_f32 v49, v167, 0x3f800000, v210
	v_fmamk_f32 v50, v167, 0x40000000, v210
	v_fmamk_f32 v51, v167, 0x40400000, v210
	v_fmamk_f32 v52, v167, 0x41000000, v210
	v_fmamk_f32 v53, v167, 0x41100000, v210
	v_fmamk_f32 v54, v167, 0x41200000, v210
	v_fmamk_f32 v55, v167, 0x41300000, v210
	v_fmamk_f32 v56, v167, 0x41800000, v210
	v_fmamk_f32 v57, v167, 0x41880000, v210
	v_fmamk_f32 v58, v167, 0x41900000, v210
	v_fmamk_f32 v59, v167, 0x41980000, v210
	v_fmamk_f32 v60, v167, 0x41c00000, v210
	v_fmamk_f32 v61, v167, 0x41c80000, v210
	v_fmamk_f32 v62, v167, 0x41d00000, v210
	v_fmamk_f32 v63, v167, 0x41d80000, v210
	v_fmamk_f32 v32, v167, 0x42000000, v210
	v_fmamk_f32 v33, v167, 0x42040000, v210
	v_fmamk_f32 v34, v167, 0x42080000, v210
	v_fmamk_f32 v35, v167, 0x420c0000, v210
	v_fmamk_f32 v36, v167, 0x42200000, v210
	v_fmamk_f32 v37, v167, 0x42240000, v210
	v_fmamk_f32 v38, v167, 0x42280000, v210
	v_fmamk_f32 v39, v167, 0x422c0000, v210
	v_fmamk_f32 v40, v167, 0x42400000, v210
	v_fmamk_f32 v41, v167, 0x42440000, v210
	v_fmamk_f32 v42, v167, 0x42480000, v210
	v_fmamk_f32 v43, v167, 0x424c0000, v210
	v_fmamk_f32 v44, v167, 0x42600000, v210
	v_fmamk_f32 v45, v167, 0x42640000, v210
	v_fmamk_f32 v46, v167, 0x42680000, v210
	v_fmamk_f32 v47, v167, 0x426c0000, v210
	s_waitcnt vmcnt(7) lgkmcnt(3)
	v_mfma_f32_32x32x16_bf16 v[48:63], v[202:205], v[64:67], v[48:63]
	s_waitcnt lgkmcnt(2)
	v_mfma_f32_32x32x16_bf16 v[32:47], v[206:209], v[64:67], v[32:47]
	s_waitcnt vmcnt(6) lgkmcnt(0)
	v_mfma_f32_32x32x16_bf16 v[32:47], v[114:117], v[68:71], v[32:47]
	v_mfma_f32_32x32x16_bf16 v[48:63], v[110:113], v[68:71], v[48:63]
	ds_read_b128 v[110:113], v118 offset:4096
	ds_read_b128 v[114:117], v118 offset:4608
	s_waitcnt vmcnt(5) lgkmcnt(0)
	v_mfma_f32_32x32x16_bf16 v[32:47], v[114:117], v[72:75], v[32:47]
	v_mfma_f32_32x32x16_bf16 v[48:63], v[110:113], v[72:75], v[48:63]
	ds_read_b128 v[110:113], v118 offset:6144
	ds_read_b128 v[114:117], v118 offset:6656
	ds_read_b64_tr_b16 v[214:215], v134 offset:32768
	ds_read_b64_tr_b16 v[216:217], v134 offset:33280
	ds_read_b64_tr_b16 v[218:219], v134 offset:33792
	ds_read_b64_tr_b16 v[220:221], v134 offset:34304
	ds_read_b64_tr_b16 v[222:223], v134 offset:34816
	ds_read_b64_tr_b16 v[224:225], v134 offset:35328
	ds_read_b64_tr_b16 v[226:227], v134 offset:35840
	ds_read_b64_tr_b16 v[228:229], v134 offset:36352
	ds_read_b64_tr_b16 v[230:231], v134 offset:36864
	ds_read_b64_tr_b16 v[232:233], v134 offset:37376
	ds_read_b64_tr_b16 v[234:235], v134 offset:37888
	ds_read_b64_tr_b16 v[236:237], v134 offset:38400
	ds_read_b64_tr_b16 v[238:239], v134 offset:38912
	ds_read_b64_tr_b16 v[240:241], v134 offset:39424
	ds_read_b64_tr_b16 v[242:243], v134 offset:39936
	ds_read_b64_tr_b16 v[244:245], v134 offset:40448
	s_waitcnt vmcnt(4) lgkmcnt(15)
	v_mfma_f32_32x32x16_bf16 v[32:47], v[114:117], v[76:79], v[32:47]
	v_mfma_f32_32x32x16_bf16 v[48:63], v[110:113], v[76:79], v[48:63]
	s_nop 11
	v_exp_f32_e32 v32, v32
	v_exp_f32_e32 v110, v52
	v_exp_f32_e32 v112, v36
	v_exp_f32_e32 v111, v53
	v_exp_f32_e32 v113, v37
	v_exp_f32_e32 v114, v54
	v_exp_f32_e32 v116, v38
	v_exp_f32_e32 v115, v55
	v_exp_f32_e32 v117, v39
	v_exp_f32_e32 v118, v56
	v_exp_f32_e32 v120, v40
	v_exp_f32_e32 v119, v57
	v_exp_f32_e32 v121, v41
	v_exp_f32_e32 v122, v58
	v_exp_f32_e32 v124, v42
	v_exp_f32_e32 v123, v59
	v_exp_f32_e32 v125, v43
	v_exp_f32_e32 v126, v60
	v_exp_f32_e32 v128, v44
	v_exp_f32_e32 v127, v61
	v_exp_f32_e32 v129, v45
	v_exp_f32_e32 v48, v48
	v_exp_f32_e32 v49, v49
	v_exp_f32_e32 v50, v50
	v_exp_f32_e32 v51, v51
	v_exp_f32_e32 v130, v62
	v_exp_f32_e32 v132, v46
	v_exp_f32_e32 v131, v63
	v_cvt_pk_bf16_f32 v36, v48, v49
	v_cvt_pk_bf16_f32 v37, v50, v51
	v_cvt_pk_bf16_f32 v38, v110, v111
	v_cvt_pk_bf16_f32 v39, v114, v115
	s_waitcnt lgkmcnt(0)
	s_nop 0
	v_mfma_f32_32x32x16_bf16 v[16:31], v[36:39], v[214:217], v[16:31]
	v_cvt_pk_bf16_f32 v52, v118, v119
	v_cvt_pk_bf16_f32 v53, v122, v123
	v_cvt_pk_bf16_f32 v54, v126, v127
	v_cvt_pk_bf16_f32 v55, v130, v131
	v_exp_f32_e32 v33, v33
	v_exp_f32_e32 v34, v34
	v_exp_f32_e32 v35, v35
	s_waitcnt lgkmcnt(0)
	v_mfma_f32_32x32x16_bf16 v[16:31], v[52:55], v[218:221], v[16:31]
	v_exp_f32_e32 v133, v47
	v_cvt_pk_bf16_f32 v40, v32, v33
	v_cvt_pk_bf16_f32 v41, v34, v35
	v_cvt_pk_bf16_f32 v42, v112, v113
	v_cvt_pk_bf16_f32 v43, v116, v117
	s_waitcnt lgkmcnt(0)
	s_nop 0
	v_mfma_f32_32x32x16_bf16 v[16:31], v[40:43], v[222:225], v[16:31]
	v_cvt_pk_bf16_f32 v56, v120, v121
	v_cvt_pk_bf16_f32 v57, v124, v125
	v_cvt_pk_bf16_f32 v58, v128, v129
	v_cvt_pk_bf16_f32 v59, v132, v133
	s_waitcnt lgkmcnt(0)
	s_nop 0
	v_mfma_f32_32x32x16_bf16 v[16:31], v[56:59], v[226:229], v[16:31]
	s_waitcnt lgkmcnt(2)
	v_mfma_f32_32x32x16_bf16 v[0:15], v[36:39], v[230:233], v[0:15]
	v_add_f32_e64 v36, v48, 0
	v_add_f32_e64 v37, v49, 0
	v_add_f32_e64 v32, v32, v36
	v_add_f32_e64 v33, v33, v37
	v_add_f32_e64 v32, v50, v32
	v_add_f32_e64 v33, v51, v33
	v_pk_add_f32 v[32:33], v[34:35], v[32:33]
	s_waitcnt lgkmcnt(0)
	v_mfma_f32_32x32x16_bf16 v[0:15], v[52:55], v[234:237], v[0:15]
	v_add_f32_e64 v32, v110, v32
	v_add_f32_e64 v33, v111, v33
	v_add_f32_e64 v32, v112, v32
	v_add_f32_e64 v33, v113, v33
	v_add_f32_e64 v32, v114, v32
	v_add_f32_e64 v33, v115, v33
	v_pk_add_f32 v[36:37], v[116:117], v[32:33]
	s_waitcnt lgkmcnt(0)
	v_mfma_f32_32x32x16_bf16 v[0:15], v[40:43], v[238:241], v[0:15]
	v_add_f32_e64 v36, v118, v36
	v_add_f32_e64 v37, v119, v37
	v_add_f32_e64 v44, v120, v36
	v_add_f32_e64 v45, v121, v37
	v_pk_add_f32 v[32:33], v[122:123], v[44:45]
	s_nop 0
	v_pk_add_f32 v[32:33], v[124:125], v[32:33]
	s_waitcnt lgkmcnt(0)
	v_mfma_f32_32x32x16_bf16 v[0:15], v[56:59], v[242:245], v[0:15]
	v_add_f32_e64 v32, v126, v32
	v_add_f32_e64 v33, v127, v33
	v_add_f32_e64 v32, v128, v32
	v_add_f32_e64 v33, v129, v33
	v_add_f32_e64 v32, v130, v32
	v_add_f32_e64 v33, v131, v33
	v_pk_add_f32 v[32:33], v[132:133], v[32:33]
	s_nop 0
	v_add_f32_e32 v32, v32, v33
	v_add_f32_e32 v109, v109, v32
	s_branch .LBB0_433

; template <int TYPE> __device__ __forceinline__ void attn_unit(const AttnCtx& C, int b, int h, int qb, LAS unsigned char* lds, int tid_in, unsigned* counter) {
;     ...
;             const bool active = (TYPE == 2) ? (t >= cq - 8 && t <= cq) : (TYPE == 0) ? (t <= cq && (float)(256 * qb + 32 * w - 64 * t - 63) < dmax) : (t <= cq && t >= tfirst);
;             if (active) {
;                 f32x16 p0, p1;
;                 const LAS unsigned char* kp = Kb + bo + hi * 1024 + r32 * 16;
; #pragma unroll
;                 for (int d0 = 0; d0 < 4; ++d0) {
;                     const bf16x8 a0 = *(const LAS bf16x8*)(kp + d0 * 2048), a1 = *(const LAS bf16x8*)(kp + d0 * 2048 + 512);
;                     if (d0 == 0) { p0 = MFMA32(a0, qr[0], (TYPE == 1 ? cvec : zvec)); p1 = MFMA32(a1, qr[0], (TYPE == 1 ? cvec : zvec)); }
;                     else { p0 = MFMA32(a0, qr[d0], p0); p1 = MFMA32(a1, qr[d0], p1); }
;                 }
;                 const int xi = sq - 64 * t - 4 * hi;
;                 if (TYPE == 0) {
;                     const float xf = (float)xi;
; #pragma unroll
;                     for (int r = 0; r < 16; ++r) { const float c = (float)((r & 3) + 8 * (r >> 2));
;                         p0[r] = fast_exp2(p0[r] - sl2 * fabsf(xf - c)); p1[r] = fast_exp2(p1[r] - sl2 * fabsf(xf - (c + 32.f))); }
;                 } else if (TYPE == 1) {
;                     const LAS float* fp = Fb + (t & 3) * 64 + 4 * hi;
; #pragma unroll
;                     for (int g = 0; g < 4; ++g) { const f32x4 fa = *(const LAS f32x4*)(fp + 8 * g), fb2 = *(const LAS f32x4*)(fp + 32 + 8 * g);
; #pragma unroll
;                         for (int i = 0; i < 4; i += 2) {
;                             const f32x2_t d0_ = (f32x2_t){p0[4 * g + i], p0[4 * g + i + 1]} - (f32x2_t){fa[i], fa[i + 1]}, d1_ = (f32x2_t){p1[4 * g + i], p1[4 * g + i + 1]} - (f32x2_t){fb2[i], fb2[i + 1]};
;                             p0[4 * g + i] = fast_exp2(d0_[0]); p0[4 * g + i + 1] = fast_exp2(d0_[1]); p1[4 * g + i] = fast_exp2(d1_[0]); p1[4 * g + i + 1] = fast_exp2(d1_[1]); } }
;                     if (t == cq) { const int qrel = 32 * (w & 1) + r32;
; #pragma unroll
;                         for (int r = 0; r < 16; ++r) { const int kv = crow(r, hi); if (kv > qrel) p0[r] = 0.f; if (kv + 32 > qrel) p1[r] = 0.f; } }
;                 } else {
;                     if (cq - t >= 3) { const float bc = relb[256];
.LBB0_454:
	s_cmp_gt_i32 s15, s14
	s_cbranch_scc1 .LBB0_445
	s_sub_i32 s0, s6, 63
	s_waitcnt vmcnt(15)
	v_cvt_f32_i32_e32 v64, s0
	v_cmp_ngt_f32_e32 vcc, v168, v64
	s_cbranch_vccnz .LBB0_445
	s_cmp_eq_u32 s15, s14
	s_cbranch_scc1 .Lt0diag_3
	v_add_u32_e32 v184, s16, v171
	v_add_u32_e32 v213, s6, v172
	v_cvt_f32_i32_e32 v213, v213
	v_mul_f32_e64 v210, -v167, v213
	ds_read_b128 v[202:205], v184
	s_waitcnt vmcnt(14)
	ds_read_b128 v[206:209], v184 offset:512
	ds_read_b128 v[176:179], v184 offset:2048
	ds_read_b128 v[180:183], v184 offset:2560
	v_add_u32_e32 v200, s16, v170
	v_mov_b32_e32 v80, v210
	v_fmamk_f32 v81, v167, 0x3f800000, v210
	v_fmamk_f32 v82, v167, 0x40000000, v210
	v_fmamk_f32 v83, v167, 0x40400000, v210
	v_fmamk_f32 v84, v167, 0x41000000, v210
	v_fmamk_f32 v85, v167, 0x41100000, v210
	v_fmamk_f32 v86, v167, 0x41200000, v210
	v_fmamk_f32 v87, v167, 0x41300000, v210
	v_fmamk_f32 v88, v167, 0x41800000, v210
	v_fmamk_f32 v89, v167, 0x41880000, v210
	v_fmamk_f32 v90, v167, 0x41900000, v210
	v_fmamk_f32 v91, v167, 0x41980000, v210
	v_fmamk_f32 v92, v167, 0x41c00000, v210
	v_fmamk_f32 v93, v167, 0x41c80000, v210
	v_fmamk_f32 v94, v167, 0x41d00000, v210
	v_fmamk_f32 v95, v167, 0x41d80000, v210
	v_fmamk_f32 v64, v167, 0x42000000, v210
	v_fmamk_f32 v65, v167, 0x42040000, v210
	v_fmamk_f32 v66, v167, 0x42080000, v210
	v_fmamk_f32 v67, v167, 0x420c0000, v210
	v_fmamk_f32 v68, v167, 0x42200000, v210
	v_fmamk_f32 v69, v167, 0x42240000, v210
	v_fmamk_f32 v70, v167, 0x42280000, v210
	v_fmamk_f32 v71, v167, 0x422c0000, v210
	v_fmamk_f32 v72, v167, 0x42400000, v210
	v_fmamk_f32 v73, v167, 0x42440000, v210
	v_fmamk_f32 v74, v167, 0x42480000, v210
	v_fmamk_f32 v75, v167, 0x424c0000, v210
	v_fmamk_f32 v76, v167, 0x42600000, v210
	v_fmamk_f32 v77, v167, 0x42640000, v210
	v_fmamk_f32 v78, v167, 0x42680000, v210
	v_fmamk_f32 v79, v167, 0x426c0000, v210
	s_waitcnt vmcnt(7) lgkmcnt(3)
	v_mfma_f32_32x32x16_bf16 v[80:95], v[202:205], v[112:115], v[80:95]
	s_waitcnt lgkmcnt(2)
	v_mfma_f32_32x32x16_bf16 v[64:79], v[206:209], v[112:115], v[64:79]
	s_waitcnt vmcnt(6) lgkmcnt(0)
	v_mfma_f32_32x32x16_bf16 v[64:79], v[180:183], v[116:119], v[64:79]
	v_mfma_f32_32x32x16_bf16 v[80:95], v[176:179], v[116:119], v[80:95]
	ds_read_b128 v[176:179], v184 offset:4096
	ds_read_b128 v[180:183], v184 offset:4608
	s_waitcnt vmcnt(5) lgkmcnt(0)
	v_mfma_f32_32x32x16_bf16 v[64:79], v[180:183], v[120:123], v[64:79]
	v_mfma_f32_32x32x16_bf16 v[80:95], v[176:179], v[120:123], v[80:95]
	ds_read_b128 v[176:179], v184 offset:6144
	ds_read_b128 v[180:183], v184 offset:6656
	ds_read_b64_tr_b16 v[214:215], v200 offset:32768
	ds_read_b64_tr_b16 v[216:217], v200 offset:33280
	ds_read_b64_tr_b16 v[218:219], v200 offset:33792
	ds_read_b64_tr_b16 v[220:221], v200 offset:34304
	ds_read_b64_tr_b16 v[222:223], v200 offset:34816
	ds_read_b64_tr_b16 v[224:225], v200 offset:35328
	ds_read_b64_tr_b16 v[226:227], v200 offset:35840
	ds_read_b64_tr_b16 v[228:229], v200 offset:36352
	ds_read_b64_tr_b16 v[230:231], v200 offset:36864
	ds_read_b64_tr_b16 v[232:233], v200 offset:37376
	ds_read_b64_tr_b16 v[234:235], v200 offset:37888
	ds_read_b64_tr_b16 v[236:237], v200 offset:38400
	ds_read_b64_tr_b16 v[238:239], v200 offset:38912
	ds_read_b64_tr_b16 v[240:241], v200 offset:39424
	ds_read_b64_tr_b16 v[242:243], v200 offset:39936
	ds_read_b64_tr_b16 v[244:245], v200 offset:40448
	s_waitcnt vmcnt(4) lgkmcnt(15)
	v_mfma_f32_32x32x16_bf16 v[64:79], v[180:183], v[124:127], v[64:79]
	v_mfma_f32_32x32x16_bf16 v[80:95], v[176:179], v[124:127], v[80:95]
	s_nop 11
	v_exp_f32_e32 v64, v64
	v_exp_f32_e32 v176, v84
	v_exp_f32_e32 v178, v68
	v_exp_f32_e32 v177, v85
	v_exp_f32_e32 v179, v69
	v_exp_f32_e32 v180, v86
	v_exp_f32_e32 v182, v70
	v_exp_f32_e32 v181, v87
	v_exp_f32_e32 v183, v71
	v_exp_f32_e32 v184, v88
	v_exp_f32_e32 v186, v72
	v_exp_f32_e32 v185, v89
	v_exp_f32_e32 v187, v73
	v_exp_f32_e32 v188, v90
	v_exp_f32_e32 v190, v74
	v_exp_f32_e32 v189, v91
	v_exp_f32_e32 v191, v75
	v_exp_f32_e32 v192, v92
	v_exp_f32_e32 v194, v76
	v_exp_f32_e32 v193, v93
	v_exp_f32_e32 v195, v77
	v_exp_f32_e32 v80, v80
	v_exp_f32_e32 v81, v81
	v_exp_f32_e32 v82, v82
	v_exp_f32_e32 v83, v83
	v_exp_f32_e32 v196, v94
	v_exp_f32_e32 v198, v78
	v_exp_f32_e32 v197, v95
	v_cvt_pk_bf16_f32 v68, v80, v81
	v_cvt_pk_bf16_f32 v69, v82, v83
	v_cvt_pk_bf16_f32 v70, v176, v177
	v_cvt_pk_bf16_f32 v71, v180, v181
	s_waitcnt lgkmcnt(0)
	s_nop 0
	v_mfma_f32_32x32x16_bf16 v[48:63], v[68:71], v[214:217], v[48:63]
	v_cvt_pk_bf16_f32 v84, v184, v185
	v_cvt_pk_bf16_f32 v85, v188, v189
	v_cvt_pk_bf16_f32 v86, v192, v193
	v_cvt_pk_bf16_f32 v87, v196, v197
	v_exp_f32_e32 v65, v65
	v_exp_f32_e32 v66, v66
	v_exp_f32_e32 v67, v67
	s_waitcnt lgkmcnt(0)
	v_mfma_f32_32x32x16_bf16 v[48:63], v[84:87], v[218:221], v[48:63]
	v_exp_f32_e32 v199, v79
	v_cvt_pk_bf16_f32 v72, v64, v65
	v_cvt_pk_bf16_f32 v73, v66, v67
	v_cvt_pk_bf16_f32 v74, v178, v179
	v_cvt_pk_bf16_f32 v75, v182, v183
	s_waitcnt lgkmcnt(0)
	s_nop 0
	v_mfma_f32_32x32x16_bf16 v[48:63], v[72:75], v[222:225], v[48:63]
	v_cvt_pk_bf16_f32 v88, v186, v187
	v_cvt_pk_bf16_f32 v89, v190, v191
	v_cvt_pk_bf16_f32 v90, v194, v195
	v_cvt_pk_bf16_f32 v91, v198, v199
	s_waitcnt lgkmcnt(0)
	s_nop 0
	v_mfma_f32_32x32x16_bf16 v[48:63], v[88:91], v[226:229], v[48:63]
	s_waitcnt lgkmcnt(2)
	v_mfma_f32_32x32x16_bf16 v[32:47], v[68:71], v[230:233], v[32:47]
	v_add_f32_e64 v68, v80, 0
	v_add_f32_e64 v69, v81, 0
	v_add_f32_e64 v64, v64, v68
	v_add_f32_e64 v65, v65, v69
	v_add_f32_e64 v64, v82, v64
	v_add_f32_e64 v65, v83, v65
	v_pk_add_f32 v[64:65], v[66:67], v[64:65]
	s_waitcnt lgkmcnt(0)
	v_mfma_f32_32x32x16_bf16 v[32:47], v[84:87], v[234:237], v[32:47]
	v_add_f32_e64 v64, v176, v64
	v_add_f32_e64 v65, v177, v65
	v_add_f32_e64 v64, v178, v64
	v_add_f32_e64 v65, v179, v65
	v_add_f32_e64 v64, v180, v64
	v_add_f32_e64 v65, v181, v65
	v_pk_add_f32 v[68:69], v[182:183], v[64:65]
	s_waitcnt lgkmcnt(0)
	v_mfma_f32_32x32x16_bf16 v[32:47], v[72:75], v[238:241], v[32:47]
	v_add_f32_e64 v68, v184, v68
	v_add_f32_e64 v69, v185, v69
	v_add_f32_e64 v76, v186, v68
	v_add_f32_e64 v77, v187, v69
	v_pk_add_f32 v[64:65], v[188:189], v[76:77]
	s_nop 0
	v_pk_add_f32 v[64:65], v[190:191], v[64:65]
	s_waitcnt lgkmcnt(0)
	v_mfma_f32_32x32x16_bf16 v[32:47], v[88:91], v[242:245], v[32:47]
	v_add_f32_e64 v64, v192, v64
	v_add_f32_e64 v65, v193, v65
	v_add_f32_e64 v64, v194, v64
	v_add_f32_e64 v65, v195, v65
	v_add_f32_e64 v64, v196, v64
	v_add_f32_e64 v65, v197, v65
	v_pk_add_f32 v[64:65], v[198:199], v[64:65]
	s_nop 0
	v_add_f32_e32 v64, v64, v65
	v_add_f32_e32 v175, v175, v64
	s_branch .LBB0_445

; template <int TYPE> __device__ __forceinline__ void attn_unit(const AttnCtx& C, int b, int h, int qb, LAS unsigned char* lds, int tid_in, unsigned* counter) {
;     ...
;             const bool active = (TYPE == 2) ? (t >= cq - 8 && t <= cq) : (TYPE == 0) ? (t <= cq && (float)(256 * qb + 32 * w - 64 * t - 63) < dmax) : (t <= cq && t >= tfirst);
;             if (active) {
;                 f32x16 p0, p1;
;                 const LAS unsigned char* kp = Kb + bo + hi * 1024 + r32 * 16;
; #pragma unroll
;                 for (int d0 = 0; d0 < 4; ++d0) {
;                     const bf16x8 a0 = *(const LAS bf16x8*)(kp + d0 * 2048), a1 = *(const LAS bf16x8*)(kp + d0 * 2048 + 512);
;                     if (d0 == 0) { p0 = MFMA32(a0, qr[0], (TYPE == 1 ? cvec : zvec)); p1 = MFMA32(a1, qr[0], (TYPE == 1 ? cvec : zvec)); }
;                     else { p0 = MFMA32(a0, qr[d0], p0); p1 = MFMA32(a1, qr[d0], p1); }
;                 }
;                 const int xi = sq - 64 * t - 4 * hi;
;                 if (TYPE == 0) {
;                     const float xf = (float)xi;
; #pragma unroll
;                     for (int r = 0; r < 16; ++r) { const float c = (float)((r & 3) + 8 * (r >> 2));
;                         p0[r] = fast_exp2(p0[r] - sl2 * fabsf(xf - c)); p1[r] = fast_exp2(p1[r] - sl2 * fabsf(xf - (c + 32.f))); }
;                 } else if (TYPE == 1) {
;                     const LAS float* fp = Fb + (t & 3) * 64 + 4 * hi;
; #pragma unroll
;                     for (int g = 0; g < 4; ++g) { const f32x4 fa = *(const LAS f32x4*)(fp + 8 * g), fb2 = *(const LAS f32x4*)(fp + 32 + 8 * g);
; #pragma unroll
;                         for (int i = 0; i < 4; i += 2) {
;                             const f32x2_t d0_ = (f32x2_t){p0[4 * g + i], p0[4 * g + i + 1]} - (f32x2_t){fa[i], fa[i + 1]}, d1_ = (f32x2_t){p1[4 * g + i], p1[4 * g + i + 1]} - (f32x2_t){fb2[i], fb2[i + 1]};
;                             p0[4 * g + i] = fast_exp2(d0_[0]); p0[4 * g + i + 1] = fast_exp2(d0_[1]); p1[4 * g + i] = fast_exp2(d1_[0]); p1[4 * g + i + 1] = fast_exp2(d1_[1]); } }
;                     if (t == cq) { const int qrel = 32 * (w & 1) + r32;
; #pragma unroll
;                         for (int r = 0; r < 16; ++r) { const int kv = crow(r, hi); if (kv > qrel) p0[r] = 0.f; if (kv + 32 > qrel) p1[r] = 0.f; } }
;                 } else {
;                     if (cq - t >= 3) { const float bc = relb[256];
.LBB0_1364:
	s_cmp_gt_i32 s3, s12
	s_cbranch_scc1 .LBB0_1359
	s_sub_i32 s7, s0, 63
	v_cvt_f32_i32_e32 v32, s7
	v_cmp_ngt_f32_e32 vcc, v168, v32
	s_cbranch_vccnz .LBB0_1359
	s_cmp_eq_u32 s3, s12
	s_cbranch_scc1 .Lt0diag_2
	v_add_u32_e32 v118, s6, v171
	v_add_u32_e32 v213, s0, v172
	v_cvt_f32_i32_e32 v213, v213
	v_mul_f32_e64 v210, -v167, v213
	ds_read_b128 v[202:205], v118
	ds_read_b128 v[206:209], v118 offset:512
	ds_read_b128 v[110:113], v118 offset:2048
	ds_read_b128 v[114:117], v118 offset:2560
	v_add_u32_e32 v134, s6, v170
	v_mov_b32_e32 v48, v210
	v_fmamk_f32 v49, v167, 0x3f800000, v210
	v_fmamk_f32 v50, v167, 0x40000000, v210
	v_fmamk_f32 v51, v167, 0x40400000, v210
	v_fmamk_f32 v52, v167, 0x41000000, v210
	v_fmamk_f32 v53, v167, 0x41100000, v210
	v_fmamk_f32 v54, v167, 0x41200000, v210
	v_fmamk_f32 v55, v167, 0x41300000, v210
	v_fmamk_f32 v56, v167, 0x41800000, v210
	v_fmamk_f32 v57, v167, 0x41880000, v210
	v_fmamk_f32 v58, v167, 0x41900000, v210
	v_fmamk_f32 v59, v167, 0x41980000, v210
	v_fmamk_f32 v60, v167, 0x41c00000, v210
	v_fmamk_f32 v61, v167, 0x41c80000, v210
	v_fmamk_f32 v62, v167, 0x41d00000, v210
	v_fmamk_f32 v63, v167, 0x41d80000, v210
	v_fmamk_f32 v32, v167, 0x42000000, v210
	v_fmamk_f32 v33, v167, 0x42040000, v210
	v_fmamk_f32 v34, v167, 0x42080000, v210
	v_fmamk_f32 v35, v167, 0x420c0000, v210
	v_fmamk_f32 v36, v167, 0x42200000, v210
	v_fmamk_f32 v37, v167, 0x42240000, v210
	v_fmamk_f32 v38, v167, 0x42280000, v210
	v_fmamk_f32 v39, v167, 0x422c0000, v210
	v_fmamk_f32 v40, v167, 0x42400000, v210
	v_fmamk_f32 v41, v167, 0x42440000, v210
	v_fmamk_f32 v42, v167, 0x42480000, v210
	v_fmamk_f32 v43, v167, 0x424c0000, v210
	v_fmamk_f32 v44, v167, 0x42600000, v210
	v_fmamk_f32 v45, v167, 0x42640000, v210
	v_fmamk_f32 v46, v167, 0x42680000, v210
	v_fmamk_f32 v47, v167, 0x426c0000, v210
	s_waitcnt vmcnt(7) lgkmcnt(3)
	v_mfma_f32_32x32x16_bf16 v[48:63], v[202:205], v[64:67], v[48:63]
	s_waitcnt lgkmcnt(2)
	v_mfma_f32_32x32x16_bf16 v[32:47], v[206:209], v[64:67], v[32:47]
	s_waitcnt vmcnt(6) lgkmcnt(0)
	v_mfma_f32_32x32x16_bf16 v[32:47], v[114:117], v[68:71], v[32:47]
	v_mfma_f32_32x32x16_bf16 v[48:63], v[110:113], v[68:71], v[48:63]
	ds_read_b128 v[110:113], v118 offset:4096
	ds_read_b128 v[114:117], v118 offset:4608
	s_waitcnt vmcnt(5) lgkmcnt(0)
	v_mfma_f32_32x32x16_bf16 v[32:47], v[114:117], v[72:75], v[32:47]
	v_mfma_f32_32x32x16_bf16 v[48:63], v[110:113], v[72:75], v[48:63]
	ds_read_b128 v[110:113], v118 offset:6144
	ds_read_b128 v[114:117], v118 offset:6656
	ds_read_b64_tr_b16 v[214:215], v134 offset:32768
	ds_read_b64_tr_b16 v[216:217], v134 offset:33280
	ds_read_b64_tr_b16 v[218:219], v134 offset:33792
	ds_read_b64_tr_b16 v[220:221], v134 offset:34304
	ds_read_b64_tr_b16 v[222:223], v134 offset:34816
	ds_read_b64_tr_b16 v[224:225], v134 offset:35328
	ds_read_b64_tr_b16 v[226:227], v134 offset:35840
	ds_read_b64_tr_b16 v[228:229], v134 offset:36352
	ds_read_b64_tr_b16 v[230:231], v134 offset:36864
	ds_read_b64_tr_b16 v[232:233], v134 offset:37376
	ds_read_b64_tr_b16 v[234:235], v134 offset:37888
	ds_read_b64_tr_b16 v[236:237], v134 offset:38400
	ds_read_b64_tr_b16 v[238:239], v134 offset:38912
	ds_read_b64_tr_b16 v[240:241], v134 offset:39424
	ds_read_b64_tr_b16 v[242:243], v134 offset:39936
	ds_read_b64_tr_b16 v[244:245], v134 offset:40448
	s_waitcnt vmcnt(4) lgkmcnt(15)
	v_mfma_f32_32x32x16_bf16 v[32:47], v[114:117], v[76:79], v[32:47]
	v_mfma_f32_32x32x16_bf16 v[48:63], v[110:113], v[76:79], v[48:63]
	s_nop 11
	v_exp_f32_e32 v32, v32
	v_exp_f32_e32 v110, v52
	v_exp_f32_e32 v112, v36
	v_exp_f32_e32 v111, v53
	v_exp_f32_e32 v113, v37
	v_exp_f32_e32 v114, v54
	v_exp_f32_e32 v116, v38
	v_exp_f32_e32 v115, v55
	v_exp_f32_e32 v117, v39
	v_exp_f32_e32 v118, v56
	v_exp_f32_e32 v120, v40
	v_exp_f32_e32 v119, v57
	v_exp_f32_e32 v121, v41
	v_exp_f32_e32 v122, v58
	v_exp_f32_e32 v124, v42
	v_exp_f32_e32 v123, v59
	v_exp_f32_e32 v125, v43
	v_exp_f32_e32 v126, v60
	v_exp_f32_e32 v128, v44
	v_exp_f32_e32 v127, v61
	v_exp_f32_e32 v129, v45
	v_exp_f32_e32 v48, v48
	v_exp_f32_e32 v49, v49
	v_exp_f32_e32 v50, v50
	v_exp_f32_e32 v51, v51
	v_exp_f32_e32 v130, v62
	v_exp_f32_e32 v132, v46
	v_exp_f32_e32 v131, v63
	v_cvt_pk_bf16_f32 v36, v48, v49
	v_cvt_pk_bf16_f32 v37, v50, v51
	v_cvt_pk_bf16_f32 v38, v110, v111
	v_cvt_pk_bf16_f32 v39, v114, v115
	s_waitcnt lgkmcnt(0)
	s_nop 0
	v_mfma_f32_32x32x16_bf16 v[16:31], v[36:39], v[214:217], v[16:31]
	v_cvt_pk_bf16_f32 v52, v118, v119
	v_cvt_pk_bf16_f32 v53, v122, v123
	v_cvt_pk_bf16_f32 v54, v126, v127
	v_cvt_pk_bf16_f32 v55, v130, v131
	v_exp_f32_e32 v33, v33
	v_exp_f32_e32 v34, v34
	v_exp_f32_e32 v35, v35
	s_waitcnt lgkmcnt(0)
	v_mfma_f32_32x32x16_bf16 v[16:31], v[52:55], v[218:221], v[16:31]
	v_exp_f32_e32 v133, v47
	v_cvt_pk_bf16_f32 v40, v32, v33
	v_cvt_pk_bf16_f32 v41, v34, v35
	v_cvt_pk_bf16_f32 v42, v112, v113
	v_cvt_pk_bf16_f32 v43, v116, v117
	s_waitcnt lgkmcnt(0)
	s_nop 0
	v_mfma_f32_32x32x16_bf16 v[16:31], v[40:43], v[222:225], v[16:31]
	v_cvt_pk_bf16_f32 v56, v120, v121
	v_cvt_pk_bf16_f32 v57, v124, v125
	v_cvt_pk_bf16_f32 v58, v128, v129
	v_cvt_pk_bf16_f32 v59, v132, v133
	s_waitcnt lgkmcnt(0)
	s_nop 0
	v_mfma_f32_32x32x16_bf16 v[16:31], v[56:59], v[226:229], v[16:31]
	s_waitcnt lgkmcnt(2)
	v_mfma_f32_32x32x16_bf16 v[0:15], v[36:39], v[230:233], v[0:15]
	v_add_f32_e64 v36, v48, 0
	v_add_f32_e64 v37, v49, 0
	v_add_f32_e64 v32, v32, v36
	v_add_f32_e64 v33, v33, v37
	v_add_f32_e64 v32, v50, v32
	v_add_f32_e64 v33, v51, v33
	v_pk_add_f32 v[32:33], v[34:35], v[32:33]
	s_waitcnt lgkmcnt(0)
	v_mfma_f32_32x32x16_bf16 v[0:15], v[52:55], v[234:237], v[0:15]
	v_add_f32_e64 v32, v110, v32
	v_add_f32_e64 v33, v111, v33
	v_add_f32_e64 v32, v112, v32
	v_add_f32_e64 v33, v113, v33
	v_add_f32_e64 v32, v114, v32
	v_add_f32_e64 v33, v115, v33
	v_pk_add_f32 v[36:37], v[116:117], v[32:33]
	s_waitcnt lgkmcnt(0)
	v_mfma_f32_32x32x16_bf16 v[0:15], v[40:43], v[238:241], v[0:15]
	v_add_f32_e64 v36, v118, v36
	v_add_f32_e64 v37, v119, v37
	v_add_f32_e64 v44, v120, v36
	v_add_f32_e64 v45, v121, v37
	v_pk_add_f32 v[32:33], v[122:123], v[44:45]
	s_nop 0
	v_pk_add_f32 v[32:33], v[124:125], v[32:33]
	s_waitcnt lgkmcnt(0)
	v_mfma_f32_32x32x16_bf16 v[0:15], v[56:59], v[242:245], v[0:15]
	v_add_f32_e64 v32, v126, v32
	v_add_f32_e64 v33, v127, v33
	v_add_f32_e64 v32, v128, v32
	v_add_f32_e64 v33, v129, v33
	v_add_f32_e64 v32, v130, v32
	v_add_f32_e64 v33, v131, v33
	v_pk_add_f32 v[32:33], v[132:133], v[32:33]
	s_nop 0
	v_add_f32_e32 v32, v32, v33
	v_add_f32_e32 v109, v109, v32
	s_branch .LBB0_1359

; template <int TYPE> __device__ __forceinline__ void attn_unit(const AttnCtx& C, int b, int h, int qb, LAS unsigned char* lds, int tid_in, unsigned* counter) {
;     ...
;             const bool active = (TYPE == 2) ? (t >= cq - 8 && t <= cq) : (TYPE == 0) ? (t <= cq && (float)(256 * qb + 32 * w - 64 * t - 63) < dmax) : (t <= cq && t >= tfirst);
;             if (active) {
;                 f32x16 p0, p1;
;                 const LAS unsigned char* kp = Kb + bo + hi * 1024 + r32 * 16;
; #pragma unroll
;                 for (int d0 = 0; d0 < 4; ++d0) {
;                     const bf16x8 a0 = *(const LAS bf16x8*)(kp + d0 * 2048), a1 = *(const LAS bf16x8*)(kp + d0 * 2048 + 512);
;                     if (d0 == 0) { p0 = MFMA32(a0, qr[0], (TYPE == 1 ? cvec : zvec)); p1 = MFMA32(a1, qr[0], (TYPE == 1 ? cvec : zvec)); }
;                     else { p0 = MFMA32(a0, qr[d0], p0); p1 = MFMA32(a1, qr[d0], p1); }
;                 }
;                 const int xi = sq - 64 * t - 4 * hi;
;                 if (TYPE == 0) {
;                     const float xf = (float)xi;
; #pragma unroll
;                     for (int r = 0; r < 16; ++r) { const float c = (float)((r & 3) + 8 * (r >> 2));
;                         p0[r] = fast_exp2(p0[r] - sl2 * fabsf(xf - c)); p1[r] = fast_exp2(p1[r] - sl2 * fabsf(xf - (c + 32.f))); }
;                 } else if (TYPE == 1) {
;                     const LAS float* fp = Fb + (t & 3) * 64 + 4 * hi;
; #pragma unroll
;                     for (int g = 0; g < 4; ++g) { const f32x4 fa = *(const LAS f32x4*)(fp + 8 * g), fb2 = *(const LAS f32x4*)(fp + 32 + 8 * g);
; #pragma unroll
;                         for (int i = 0; i < 4; i += 2) {
;                             const f32x2_t d0_ = (f32x2_t){p0[4 * g + i], p0[4 * g + i + 1]} - (f32x2_t){fa[i], fa[i + 1]}, d1_ = (f32x2_t){p1[4 * g + i], p1[4 * g + i + 1]} - (f32x2_t){fb2[i], fb2[i + 1]};
;                             p0[4 * g + i] = fast_exp2(d0_[0]); p0[4 * g + i + 1] = fast_exp2(d0_[1]); p1[4 * g + i] = fast_exp2(d1_[0]); p1[4 * g + i + 1] = fast_exp2(d1_[1]); } }
;                     if (t == cq) { const int qrel = 32 * (w & 1) + r32;
; #pragma unroll
;                         for (int r = 0; r < 16; ++r) { const int kv = crow(r, hi); if (kv > qrel) p0[r] = 0.f; if (kv + 32 > qrel) p1[r] = 0.f; } }
;                 } else {
;                     if (cq - t >= 3) { const float bc = relb[256];
.LBB0_1380:
	s_cmp_gt_i32 s13, s12
	s_cbranch_scc1 .LBB0_1371
	s_sub_i32 s0, s15, 63
	s_waitcnt vmcnt(15)
	v_cvt_f32_i32_e32 v64, s0
	v_cmp_ngt_f32_e32 vcc, v168, v64
	s_cbranch_vccnz .LBB0_1371
	s_cmp_eq_u32 s13, s12
	s_cbranch_scc1 .Lt0diag_1
	v_add_u32_e32 v184, s17, v171
	v_add_u32_e32 v213, s15, v172
	v_cvt_f32_i32_e32 v213, v213
	v_mul_f32_e64 v210, -v167, v213
	ds_read_b128 v[202:205], v184
	s_waitcnt vmcnt(14)
	ds_read_b128 v[206:209], v184 offset:512
	ds_read_b128 v[176:179], v184 offset:2048
	ds_read_b128 v[180:183], v184 offset:2560
	v_add_u32_e32 v200, s17, v170
	v_mov_b32_e32 v80, v210
	v_fmamk_f32 v81, v167, 0x3f800000, v210
	v_fmamk_f32 v82, v167, 0x40000000, v210
	v_fmamk_f32 v83, v167, 0x40400000, v210
	v_fmamk_f32 v84, v167, 0x41000000, v210
	v_fmamk_f32 v85, v167, 0x41100000, v210
	v_fmamk_f32 v86, v167, 0x41200000, v210
	v_fmamk_f32 v87, v167, 0x41300000, v210
	v_fmamk_f32 v88, v167, 0x41800000, v210
	v_fmamk_f32 v89, v167, 0x41880000, v210
	v_fmamk_f32 v90, v167, 0x41900000, v210
	v_fmamk_f32 v91, v167, 0x41980000, v210
	v_fmamk_f32 v92, v167, 0x41c00000, v210
	v_fmamk_f32 v93, v167, 0x41c80000, v210
	v_fmamk_f32 v94, v167, 0x41d00000, v210
	v_fmamk_f32 v95, v167, 0x41d80000, v210
	v_fmamk_f32 v64, v167, 0x42000000, v210
	v_fmamk_f32 v65, v167, 0x42040000, v210
	v_fmamk_f32 v66, v167, 0x42080000, v210
	v_fmamk_f32 v67, v167, 0x420c0000, v210
	v_fmamk_f32 v68, v167, 0x42200000, v210
	v_fmamk_f32 v69, v167, 0x42240000, v210
	v_fmamk_f32 v70, v167, 0x42280000, v210
	v_fmamk_f32 v71, v167, 0x422c0000, v210
	v_fmamk_f32 v72, v167, 0x42400000, v210
	v_fmamk_f32 v73, v167, 0x42440000, v210
	v_fmamk_f32 v74, v167, 0x42480000, v210
	v_fmamk_f32 v75, v167, 0x424c0000, v210
	v_fmamk_f32 v76, v167, 0x42600000, v210
	v_fmamk_f32 v77, v167, 0x42640000, v210
	v_fmamk_f32 v78, v167, 0x42680000, v210
	v_fmamk_f32 v79, v167, 0x426c0000, v210
	s_waitcnt vmcnt(7) lgkmcnt(3)
	v_mfma_f32_32x32x16_bf16 v[80:95], v[202:205], v[112:115], v[80:95]
	s_waitcnt lgkmcnt(2)
	v_mfma_f32_32x32x16_bf16 v[64:79], v[206:209], v[112:115], v[64:79]
	s_waitcnt vmcnt(6) lgkmcnt(0)
	v_mfma_f32_32x32x16_bf16 v[64:79], v[180:183], v[116:119], v[64:79]
	v_mfma_f32_32x32x16_bf16 v[80:95], v[176:179], v[116:119], v[80:95]
	ds_read_b128 v[176:179], v184 offset:4096
	ds_read_b128 v[180:183], v184 offset:4608
	s_waitcnt vmcnt(5) lgkmcnt(0)
	v_mfma_f32_32x32x16_bf16 v[64:79], v[180:183], v[120:123], v[64:79]
	v_mfma_f32_32x32x16_bf16 v[80:95], v[176:179], v[120:123], v[80:95]
	ds_read_b128 v[176:179], v184 offset:6144
	ds_read_b128 v[180:183], v184 offset:6656
	ds_read_b64_tr_b16 v[214:215], v200 offset:32768
	ds_read_b64_tr_b16 v[216:217], v200 offset:33280
	ds_read_b64_tr_b16 v[218:219], v200 offset:33792
	ds_read_b64_tr_b16 v[220:221], v200 offset:34304
	ds_read_b64_tr_b16 v[222:223], v200 offset:34816
	ds_read_b64_tr_b16 v[224:225], v200 offset:35328
	ds_read_b64_tr_b16 v[226:227], v200 offset:35840
	ds_read_b64_tr_b16 v[228:229], v200 offset:36352
	ds_read_b64_tr_b16 v[230:231], v200 offset:36864
	ds_read_b64_tr_b16 v[232:233], v200 offset:37376
	ds_read_b64_tr_b16 v[234:235], v200 offset:37888
	ds_read_b64_tr_b16 v[236:237], v200 offset:38400
	ds_read_b64_tr_b16 v[238:239], v200 offset:38912
	ds_read_b64_tr_b16 v[240:241], v200 offset:39424
	ds_read_b64_tr_b16 v[242:243], v200 offset:39936
	ds_read_b64_tr_b16 v[244:245], v200 offset:40448
	s_waitcnt vmcnt(4) lgkmcnt(15)
	v_mfma_f32_32x32x16_bf16 v[64:79], v[180:183], v[124:127], v[64:79]
	v_mfma_f32_32x32x16_bf16 v[80:95], v[176:179], v[124:127], v[80:95]
	s_nop 11
	v_exp_f32_e32 v64, v64
	v_exp_f32_e32 v176, v84
	v_exp_f32_e32 v178, v68
	v_exp_f32_e32 v177, v85
	v_exp_f32_e32 v179, v69
	v_exp_f32_e32 v180, v86
	v_exp_f32_e32 v182, v70
	v_exp_f32_e32 v181, v87
	v_exp_f32_e32 v183, v71
	v_exp_f32_e32 v184, v88
	v_exp_f32_e32 v186, v72
	v_exp_f32_e32 v185, v89
	v_exp_f32_e32 v187, v73
	v_exp_f32_e32 v188, v90
	v_exp_f32_e32 v190, v74
	v_exp_f32_e32 v189, v91
	v_exp_f32_e32 v191, v75
	v_exp_f32_e32 v192, v92
	v_exp_f32_e32 v194, v76
	v_exp_f32_e32 v193, v93
	v_exp_f32_e32 v195, v77
	v_exp_f32_e32 v80, v80
	v_exp_f32_e32 v81, v81
	v_exp_f32_e32 v82, v82
	v_exp_f32_e32 v83, v83
	v_exp_f32_e32 v196, v94
	v_exp_f32_e32 v198, v78
	v_exp_f32_e32 v197, v95
	v_cvt_pk_bf16_f32 v68, v80, v81
	v_cvt_pk_bf16_f32 v69, v82, v83
	v_cvt_pk_bf16_f32 v70, v176, v177
	v_cvt_pk_bf16_f32 v71, v180, v181
	s_waitcnt lgkmcnt(0)
	s_nop 0
	v_mfma_f32_32x32x16_bf16 v[48:63], v[68:71], v[214:217], v[48:63]
	v_cvt_pk_bf16_f32 v84, v184, v185
	v_cvt_pk_bf16_f32 v85, v188, v189
	v_cvt_pk_bf16_f32 v86, v192, v193
	v_cvt_pk_bf16_f32 v87, v196, v197
	v_exp_f32_e32 v65, v65
	v_exp_f32_e32 v66, v66
	v_exp_f32_e32 v67, v67
	s_waitcnt lgkmcnt(0)
	v_mfma_f32_32x32x16_bf16 v[48:63], v[84:87], v[218:221], v[48:63]
	v_exp_f32_e32 v199, v79
	v_cvt_pk_bf16_f32 v72, v64, v65
	v_cvt_pk_bf16_f32 v73, v66, v67
	v_cvt_pk_bf16_f32 v74, v178, v179
	v_cvt_pk_bf16_f32 v75, v182, v183
	s_waitcnt lgkmcnt(0)
	s_nop 0
	v_mfma_f32_32x32x16_bf16 v[48:63], v[72:75], v[222:225], v[48:63]
	v_cvt_pk_bf16_f32 v88, v186, v187
	v_cvt_pk_bf16_f32 v89, v190, v191
	v_cvt_pk_bf16_f32 v90, v194, v195
	v_cvt_pk_bf16_f32 v91, v198, v199
	s_waitcnt lgkmcnt(0)
	s_nop 0
	v_mfma_f32_32x32x16_bf16 v[48:63], v[88:91], v[226:229], v[48:63]
	s_waitcnt lgkmcnt(2)
	v_mfma_f32_32x32x16_bf16 v[32:47], v[68:71], v[230:233], v[32:47]
	v_add_f32_e64 v68, v80, 0
	v_add_f32_e64 v69, v81, 0
	v_add_f32_e64 v64, v64, v68
	v_add_f32_e64 v65, v65, v69
	v_add_f32_e64 v64, v82, v64
	v_add_f32_e64 v65, v83, v65
	v_pk_add_f32 v[64:65], v[66:67], v[64:65]
	s_waitcnt lgkmcnt(0)
	v_mfma_f32_32x32x16_bf16 v[32:47], v[84:87], v[234:237], v[32:47]
	v_add_f32_e64 v64, v176, v64
	v_add_f32_e64 v65, v177, v65
	v_add_f32_e64 v64, v178, v64
	v_add_f32_e64 v65, v179, v65
	v_add_f32_e64 v64, v180, v64
	v_add_f32_e64 v65, v181, v65
	v_pk_add_f32 v[68:69], v[182:183], v[64:65]
	s_waitcnt lgkmcnt(0)
	v_mfma_f32_32x32x16_bf16 v[32:47], v[72:75], v[238:241], v[32:47]
	v_add_f32_e64 v68, v184, v68
	v_add_f32_e64 v69, v185, v69
	v_add_f32_e64 v76, v186, v68
	v_add_f32_e64 v77, v187, v69
	v_pk_add_f32 v[64:65], v[188:189], v[76:77]
	s_nop 0
	v_pk_add_f32 v[64:65], v[190:191], v[64:65]
	s_waitcnt lgkmcnt(0)
	v_mfma_f32_32x32x16_bf16 v[32:47], v[88:91], v[242:245], v[32:47]
	v_add_f32_e64 v64, v192, v64
	v_add_f32_e64 v65, v193, v65
	v_add_f32_e64 v64, v194, v64
	v_add_f32_e64 v65, v195, v65
	v_add_f32_e64 v64, v196, v64
	v_add_f32_e64 v65, v197, v65
	v_pk_add_f32 v[64:65], v[198:199], v[64:65]
	s_nop 0
	v_add_f32_e32 v64, v64, v65
	v_add_f32_e32 v175, v175, v64
	s_branch .LBB0_1371
